# rwkv_segcombine (critical path of L5): staging loops unrolled, LDS reads of each 4-row update step batched before the order-preserving pk_fma chain
# speedup vs baseline: 1.1525x; 1.0363x over previous
.LBB0_1062:
	v_mov_b32_e32 v88, v16
	v_add_u32_e32 v89, 0x100, v88
	v_ashrrev_i32_e32 v99, 31, v88
	v_mov_b32_e32 v98, v88
	v_lshlrev_b64 v[98:99], 2, v[98:99]
	v_ashrrev_i32_e32 v97, 31, v89
	v_mov_b32_e32 v96, v89
	v_lshlrev_b64 v[96:97], 2, v[96:97]
	v_lshl_add_u64 v[100:101], s[6:7], 0, v[98:99]
	v_lshl_add_u64 v[102:103], s[6:7], 0, v[96:97]
	global_load_dword v90, v[100:101], off
	global_load_dword v91, v[102:103], off
	v_lshl_add_u64 v[98:99], s[8:9], 0, v[98:99]
	v_lshl_add_u64 v[96:97], s[8:9], 0, v[96:97]
	v_add_co_u32_e32 v98, vcc, s16, v98
	s_nop 1
	v_addc_co_u32_e32 v99, vcc, 0, v99, vcc
	v_add_co_u32_e32 v96, vcc, s16, v96
	s_nop 1
	v_addc_co_u32_e32 v97, vcc, 0, v97, vcc
	v_lshlrev_b32_e32 v92, 2, v88
	v_add_u32_e32 v104, 0x200, v16
	v_add_u32_e32 v105, 0x100, v104
	v_ashrrev_i32_e32 v115, 31, v104
	v_mov_b32_e32 v114, v104
	v_lshlrev_b64 v[114:115], 2, v[114:115]
	v_ashrrev_i32_e32 v113, 31, v105
	v_mov_b32_e32 v112, v105
	v_lshlrev_b64 v[112:113], 2, v[112:113]
	v_lshl_add_u64 v[116:117], s[6:7], 0, v[114:115]
	v_lshl_add_u64 v[118:119], s[6:7], 0, v[112:113]
	global_load_dword v106, v[116:117], off
	global_load_dword v107, v[118:119], off
	v_lshl_add_u64 v[114:115], s[8:9], 0, v[114:115]
	v_lshl_add_u64 v[112:113], s[8:9], 0, v[112:113]
	v_add_co_u32_e32 v114, vcc, s16, v114
	s_nop 1
	v_addc_co_u32_e32 v115, vcc, 0, v115, vcc
	v_add_co_u32_e32 v112, vcc, s16, v112
	s_nop 1
	v_addc_co_u32_e32 v113, vcc, 0, v113, vcc
	v_lshlrev_b32_e32 v108, 2, v104
	v_add_u32_e32 v120, 0x400, v16
	v_add_u32_e32 v121, 0x100, v120
	v_ashrrev_i32_e32 v131, 31, v120
	v_mov_b32_e32 v130, v120
	v_lshlrev_b64 v[130:131], 2, v[130:131]
	v_ashrrev_i32_e32 v129, 31, v121
	v_mov_b32_e32 v128, v121
	v_lshlrev_b64 v[128:129], 2, v[128:129]
	v_lshl_add_u64 v[132:133], s[6:7], 0, v[130:131]
	v_lshl_add_u64 v[134:135], s[6:7], 0, v[128:129]
	global_load_dword v122, v[132:133], off
	global_load_dword v123, v[134:135], off
	v_lshl_add_u64 v[130:131], s[8:9], 0, v[130:131]
	v_lshl_add_u64 v[128:129], s[8:9], 0, v[128:129]
	v_add_co_u32_e32 v130, vcc, s16, v130
	s_nop 1
	v_addc_co_u32_e32 v131, vcc, 0, v131, vcc
	v_add_co_u32_e32 v128, vcc, s16, v128
	s_nop 1
	v_addc_co_u32_e32 v129, vcc, 0, v129, vcc
	v_lshlrev_b32_e32 v124, 2, v120
	v_add_u32_e32 v152, 0x600, v16
	v_add_u32_e32 v153, 0x100, v152
	v_ashrrev_i32_e32 v163, 31, v152
	v_mov_b32_e32 v162, v152
	v_lshlrev_b64 v[162:163], 2, v[162:163]
	v_ashrrev_i32_e32 v161, 31, v153
	v_mov_b32_e32 v160, v153
	v_lshlrev_b64 v[160:161], 2, v[160:161]
	v_lshl_add_u64 v[164:165], s[6:7], 0, v[162:163]
	v_lshl_add_u64 v[166:167], s[6:7], 0, v[160:161]
	global_load_dword v154, v[164:165], off
	global_load_dword v155, v[166:167], off
	v_lshl_add_u64 v[162:163], s[8:9], 0, v[162:163]
	v_lshl_add_u64 v[160:161], s[8:9], 0, v[160:161]
	v_add_co_u32_e32 v162, vcc, s16, v162
	s_nop 1
	v_addc_co_u32_e32 v163, vcc, 0, v163, vcc
	v_add_co_u32_e32 v160, vcc, s16, v160
	s_nop 1
	v_addc_co_u32_e32 v161, vcc, 0, v161, vcc
	v_lshlrev_b32_e32 v156, 2, v152
	s_waitcnt vmcnt(6)
	ds_write2st64_b32 v92, v90, v91 offset1:4
	global_store_dword v[98:99], v90, off
	global_store_dword v[96:97], v91, off
	s_waitcnt vmcnt(6)
	ds_write2st64_b32 v108, v106, v107 offset1:4
	global_store_dword v[114:115], v106, off
	global_store_dword v[112:113], v107, off
	s_waitcnt vmcnt(6)
	ds_write2st64_b32 v124, v122, v123 offset1:4
	global_store_dword v[130:131], v122, off
	global_store_dword v[128:129], v123, off
	s_waitcnt vmcnt(6)
	ds_write2st64_b32 v156, v154, v155 offset1:4
	global_store_dword v[162:163], v154, off
	global_store_dword v[160:161], v155, off
	v_add_u32_e32 v88, 0x800, v16
	v_add_u32_e32 v89, 0x100, v88
	v_ashrrev_i32_e32 v99, 31, v88
	v_mov_b32_e32 v98, v88
	v_lshlrev_b64 v[98:99], 2, v[98:99]
	v_ashrrev_i32_e32 v97, 31, v89
	v_mov_b32_e32 v96, v89
	v_lshlrev_b64 v[96:97], 2, v[96:97]
	v_lshl_add_u64 v[100:101], s[6:7], 0, v[98:99]
	v_lshl_add_u64 v[102:103], s[6:7], 0, v[96:97]
	global_load_dword v90, v[100:101], off
	global_load_dword v91, v[102:103], off
	v_lshl_add_u64 v[98:99], s[8:9], 0, v[98:99]
	v_lshl_add_u64 v[96:97], s[8:9], 0, v[96:97]
	v_add_co_u32_e32 v98, vcc, s16, v98
	s_nop 1
	v_addc_co_u32_e32 v99, vcc, 0, v99, vcc
	v_add_co_u32_e32 v96, vcc, s16, v96
	s_nop 1
	v_addc_co_u32_e32 v97, vcc, 0, v97, vcc
	v_lshlrev_b32_e32 v92, 2, v88
	v_add_u32_e32 v104, 0xa00, v16
	v_add_u32_e32 v105, 0x100, v104
	v_ashrrev_i32_e32 v115, 31, v104
	v_mov_b32_e32 v114, v104
	v_lshlrev_b64 v[114:115], 2, v[114:115]
	v_ashrrev_i32_e32 v113, 31, v105
	v_mov_b32_e32 v112, v105
	v_lshlrev_b64 v[112:113], 2, v[112:113]
	v_lshl_add_u64 v[116:117], s[6:7], 0, v[114:115]
	v_lshl_add_u64 v[118:119], s[6:7], 0, v[112:113]
	global_load_dword v106, v[116:117], off
	global_load_dword v107, v[118:119], off
	v_lshl_add_u64 v[114:115], s[8:9], 0, v[114:115]
	v_lshl_add_u64 v[112:113], s[8:9], 0, v[112:113]
	v_add_co_u32_e32 v114, vcc, s16, v114
	s_nop 1
	v_addc_co_u32_e32 v115, vcc, 0, v115, vcc
	v_add_co_u32_e32 v112, vcc, s16, v112
	s_nop 1
	v_addc_co_u32_e32 v113, vcc, 0, v113, vcc
	v_lshlrev_b32_e32 v108, 2, v104
	v_add_u32_e32 v120, 0xc00, v16
	v_add_u32_e32 v121, 0x100, v120
	v_ashrrev_i32_e32 v131, 31, v120
	v_mov_b32_e32 v130, v120
	v_lshlrev_b64 v[130:131], 2, v[130:131]
	v_ashrrev_i32_e32 v129, 31, v121
	v_mov_b32_e32 v128, v121
	v_lshlrev_b64 v[128:129], 2, v[128:129]
	v_lshl_add_u64 v[132:133], s[6:7], 0, v[130:131]
	v_lshl_add_u64 v[134:135], s[6:7], 0, v[128:129]
	global_load_dword v122, v[132:133], off
	global_load_dword v123, v[134:135], off
	v_lshl_add_u64 v[130:131], s[8:9], 0, v[130:131]
	v_lshl_add_u64 v[128:129], s[8:9], 0, v[128:129]
	v_add_co_u32_e32 v130, vcc, s16, v130
	s_nop 1
	v_addc_co_u32_e32 v131, vcc, 0, v131, vcc
	v_add_co_u32_e32 v128, vcc, s16, v128
	s_nop 1
	v_addc_co_u32_e32 v129, vcc, 0, v129, vcc
	v_lshlrev_b32_e32 v124, 2, v120
	v_add_u32_e32 v152, 0xe00, v16
	v_add_u32_e32 v153, 0x100, v152
	v_ashrrev_i32_e32 v163, 31, v152
	v_mov_b32_e32 v162, v152
	v_lshlrev_b64 v[162:163], 2, v[162:163]
	v_ashrrev_i32_e32 v161, 31, v153
	v_mov_b32_e32 v160, v153
	v_lshlrev_b64 v[160:161], 2, v[160:161]
	v_lshl_add_u64 v[164:165], s[6:7], 0, v[162:163]
	v_lshl_add_u64 v[166:167], s[6:7], 0, v[160:161]
	global_load_dword v154, v[164:165], off
	global_load_dword v155, v[166:167], off
	v_lshl_add_u64 v[162:163], s[8:9], 0, v[162:163]
	v_lshl_add_u64 v[160:161], s[8:9], 0, v[160:161]
	v_add_co_u32_e32 v162, vcc, s16, v162
	s_nop 1
	v_addc_co_u32_e32 v163, vcc, 0, v163, vcc
	v_add_co_u32_e32 v160, vcc, s16, v160
	s_nop 1
	v_addc_co_u32_e32 v161, vcc, 0, v161, vcc
	v_lshlrev_b32_e32 v156, 2, v152
	s_waitcnt vmcnt(6)
	ds_write2st64_b32 v92, v90, v91 offset1:4
	global_store_dword v[98:99], v90, off
	global_store_dword v[96:97], v91, off
	s_waitcnt vmcnt(6)
	ds_write2st64_b32 v108, v106, v107 offset1:4
	global_store_dword v[114:115], v106, off
	global_store_dword v[112:113], v107, off
	s_waitcnt vmcnt(6)
	ds_write2st64_b32 v124, v122, v123 offset1:4
	global_store_dword v[130:131], v122, off
	global_store_dword v[128:129], v123, off
	s_waitcnt vmcnt(6)
	ds_write2st64_b32 v156, v154, v155 offset1:4
	global_store_dword v[162:163], v154, off
	global_store_dword v[160:161], v155, off
	s_or_b64 exec, exec, s[14:15]
	v_cmp_ne_u32_e32 vcc, v2, v4
	v_lshl_add_u32 v0, v4, 8, v16
	s_orn2_b64 s[14:15], vcc, exec

.LBB0_1072:
	v_mov_b32_e32 v88, v16
	v_add_u32_e32 v89, 0x100, v88
	v_add_u32_e32 v92, s23, v88
	v_add_u32_e32 v94, s23, v89
	v_ashrrev_i32_e32 v93, 31, v92
	v_ashrrev_i32_e32 v95, 31, v94
	v_lshl_add_u64 v[92:93], v[92:93], 2, s[10:11]
	v_lshl_add_u64 v[94:95], v[94:95], 2, s[10:11]
	global_load_dword v90, v[92:93], off
	global_load_dword v91, v[94:95], off
	v_lshlrev_b32_e32 v96, 2, v88
	v_add_u32_e32 v98, 0x200, v16
	v_add_u32_e32 v99, 0x100, v98
	v_add_u32_e32 v102, s23, v98
	v_add_u32_e32 v104, s23, v99
	v_ashrrev_i32_e32 v103, 31, v102
	v_ashrrev_i32_e32 v105, 31, v104
	v_lshl_add_u64 v[102:103], v[102:103], 2, s[10:11]
	v_lshl_add_u64 v[104:105], v[104:105], 2, s[10:11]
	global_load_dword v100, v[102:103], off
	global_load_dword v101, v[104:105], off
	v_lshlrev_b32_e32 v106, 2, v98
	v_add_u32_e32 v108, 0x400, v16
	v_add_u32_e32 v109, 0x100, v108
	v_add_u32_e32 v112, s23, v108
	v_add_u32_e32 v114, s23, v109
	v_ashrrev_i32_e32 v113, 31, v112
	v_ashrrev_i32_e32 v115, 31, v114
	v_lshl_add_u64 v[112:113], v[112:113], 2, s[10:11]
	v_lshl_add_u64 v[114:115], v[114:115], 2, s[10:11]
	global_load_dword v110, v[112:113], off
	global_load_dword v111, v[114:115], off
	v_lshlrev_b32_e32 v116, 2, v108
	v_add_u32_e32 v118, 0x600, v16
	v_add_u32_e32 v119, 0x100, v118
	v_add_u32_e32 v122, s23, v118
	v_add_u32_e32 v124, s23, v119
	v_ashrrev_i32_e32 v123, 31, v122
	v_ashrrev_i32_e32 v125, 31, v124
	v_lshl_add_u64 v[122:123], v[122:123], 2, s[10:11]
	v_lshl_add_u64 v[124:125], v[124:125], 2, s[10:11]
	global_load_dword v120, v[122:123], off
	global_load_dword v121, v[124:125], off
	v_lshlrev_b32_e32 v126, 2, v118
	v_add_u32_e32 v128, 0x800, v16
	v_add_u32_e32 v129, 0x100, v128
	v_add_u32_e32 v132, s23, v128
	v_add_u32_e32 v134, s23, v129
	v_ashrrev_i32_e32 v133, 31, v132
	v_ashrrev_i32_e32 v135, 31, v134
	v_lshl_add_u64 v[132:133], v[132:133], 2, s[10:11]
	v_lshl_add_u64 v[134:135], v[134:135], 2, s[10:11]
	global_load_dword v130, v[132:133], off
	global_load_dword v131, v[134:135], off
	v_lshlrev_b32_e32 v136, 2, v128
	v_add_u32_e32 v152, 0xa00, v16
	v_add_u32_e32 v153, 0x100, v152
	v_add_u32_e32 v156, s23, v152
	v_add_u32_e32 v158, s23, v153
	v_ashrrev_i32_e32 v157, 31, v156
	v_ashrrev_i32_e32 v159, 31, v158
	v_lshl_add_u64 v[156:157], v[156:157], 2, s[10:11]
	v_lshl_add_u64 v[158:159], v[158:159], 2, s[10:11]
	global_load_dword v154, v[156:157], off
	global_load_dword v155, v[158:159], off
	v_lshlrev_b32_e32 v160, 2, v152
	v_add_u32_e32 v162, 0xc00, v16
	v_add_u32_e32 v163, 0x100, v162
	v_add_u32_e32 v166, s23, v162
	v_add_u32_e32 v168, s23, v163
	v_ashrrev_i32_e32 v167, 31, v166
	v_ashrrev_i32_e32 v169, 31, v168
	v_lshl_add_u64 v[166:167], v[166:167], 2, s[10:11]
	v_lshl_add_u64 v[168:169], v[168:169], 2, s[10:11]
	global_load_dword v164, v[166:167], off
	global_load_dword v165, v[168:169], off
	v_lshlrev_b32_e32 v170, 2, v162
	v_add_u32_e32 v204, 0xe00, v16
	v_add_u32_e32 v205, 0x100, v204
	v_add_u32_e32 v208, s23, v204
	v_add_u32_e32 v210, s23, v205
	v_ashrrev_i32_e32 v209, 31, v208
	v_ashrrev_i32_e32 v211, 31, v210
	v_lshl_add_u64 v[208:209], v[208:209], 2, s[10:11]
	v_lshl_add_u64 v[210:211], v[210:211], 2, s[10:11]
	global_load_dword v206, v[208:209], off
	global_load_dword v207, v[210:211], off
	v_lshlrev_b32_e32 v212, 2, v204
	s_waitcnt vmcnt(14)
	ds_write2st64_b32 v96, v90, v91 offset0:64 offset1:68
	s_waitcnt vmcnt(12)
	ds_write2st64_b32 v106, v100, v101 offset0:64 offset1:68
	s_waitcnt vmcnt(10)
	ds_write2st64_b32 v116, v110, v111 offset0:64 offset1:68
	s_waitcnt vmcnt(8)
	ds_write2st64_b32 v126, v120, v121 offset0:64 offset1:68
	s_waitcnt vmcnt(6)
	ds_write2st64_b32 v136, v130, v131 offset0:64 offset1:68
	s_waitcnt vmcnt(4)
	ds_write2st64_b32 v160, v154, v155 offset0:64 offset1:68
	s_waitcnt vmcnt(2)
	ds_write2st64_b32 v170, v164, v165 offset0:64 offset1:68
	s_waitcnt vmcnt(0)
	ds_write2st64_b32 v212, v206, v207 offset0:64 offset1:68
	s_or_b64 exec, exec, s[20:21]
	s_mov_b64 s[0:1], 0
	s_and_saveexec_b64 s[20:21], s[4:5]
	s_mov_b64 s[0:1], exec
	v_lshlrev_b32_e32 v1, 2, v23
	s_or_b64 exec, exec, s[20:21]
	s_orn2_b64 s[0:1], s[0:1], exec
	v_mov_b32_e32 v0, v23

.LBB0_1080:
	v_add_u32_e32 v28, s0, v19
	ds_read_b128 v[28:31], v28
	ds_read_b128 v[88:91], v27
	ds_read_b128 v[92:95], v27 offset:16
	ds_read_b128 v[96:99], v27 offset:32
	ds_read_b128 v[100:103], v27 offset:48
	ds_read_b128 v[104:107], v27 offset:256
	ds_read_b128 v[108:111], v27 offset:272
	ds_read_b128 v[112:115], v27 offset:288
	ds_read_b128 v[116:119], v27 offset:304
	ds_read_b128 v[120:123], v27 offset:512
	ds_read_b128 v[124:127], v27 offset:528
	ds_read_b128 v[128:131], v27 offset:544
	ds_read_b128 v[132:135], v27 offset:560
	ds_read_b128 v[136:139], v27 offset:768
	ds_read_b128 v[140:143], v27 offset:784
	ds_read_b128 v[152:155], v27 offset:800
	ds_read_b128 v[156:159], v27 offset:816
	s_add_i32 s0, s0, 16
	v_add_u32_e32 v27, 0x400, v27
	s_waitcnt vmcnt(0) lgkmcnt(12)
	v_pk_fma_f32 v[0:1], v[28:29], v[88:89], v[0:1] op_sel_hi:[0,1,1]
	v_pk_fma_f32 v[2:3], v[28:29], v[90:91], v[2:3] op_sel_hi:[0,1,1]
	v_pk_fma_f32 v[4:5], v[28:29], v[92:93], v[4:5] op_sel_hi:[0,1,1]
	v_pk_fma_f32 v[6:7], v[28:29], v[94:95], v[6:7] op_sel_hi:[0,1,1]
	v_pk_fma_f32 v[8:9], v[28:29], v[96:97], v[8:9] op_sel_hi:[0,1,1]
	v_pk_fma_f32 v[10:11], v[28:29], v[98:99], v[10:11] op_sel_hi:[0,1,1]
	v_pk_fma_f32 v[12:13], v[28:29], v[100:101], v[12:13] op_sel_hi:[0,1,1]
	v_pk_fma_f32 v[14:15], v[28:29], v[102:103], v[14:15] op_sel_hi:[0,1,1]
	s_waitcnt lgkmcnt(8)
	v_pk_fma_f32 v[0:1], v[28:29], v[104:105], v[0:1] op_sel:[1,0,0]
	v_pk_fma_f32 v[2:3], v[28:29], v[106:107], v[2:3] op_sel:[1,0,0]
	v_pk_fma_f32 v[4:5], v[28:29], v[108:109], v[4:5] op_sel:[1,0,0]
	v_pk_fma_f32 v[6:7], v[28:29], v[110:111], v[6:7] op_sel:[1,0,0]
	v_pk_fma_f32 v[8:9], v[28:29], v[112:113], v[8:9] op_sel:[1,0,0]
	v_pk_fma_f32 v[10:11], v[28:29], v[114:115], v[10:11] op_sel:[1,0,0]
	v_pk_fma_f32 v[12:13], v[28:29], v[116:117], v[12:13] op_sel:[1,0,0]
	v_pk_fma_f32 v[14:15], v[28:29], v[118:119], v[14:15] op_sel:[1,0,0]
	s_waitcnt lgkmcnt(4)
	v_pk_fma_f32 v[0:1], v[30:31], v[120:121], v[0:1] op_sel_hi:[0,1,1]
	v_pk_fma_f32 v[2:3], v[30:31], v[122:123], v[2:3] op_sel_hi:[0,1,1]
	v_pk_fma_f32 v[4:5], v[30:31], v[124:125], v[4:5] op_sel_hi:[0,1,1]
	v_pk_fma_f32 v[6:7], v[30:31], v[126:127], v[6:7] op_sel_hi:[0,1,1]
	v_pk_fma_f32 v[8:9], v[30:31], v[128:129], v[8:9] op_sel_hi:[0,1,1]
	v_pk_fma_f32 v[10:11], v[30:31], v[130:131], v[10:11] op_sel_hi:[0,1,1]
	v_pk_fma_f32 v[12:13], v[30:31], v[132:133], v[12:13] op_sel_hi:[0,1,1]
	v_pk_fma_f32 v[14:15], v[30:31], v[134:135], v[14:15] op_sel_hi:[0,1,1]
	s_waitcnt lgkmcnt(0)
	v_pk_fma_f32 v[0:1], v[30:31], v[136:137], v[0:1] op_sel:[1,0,0]
	v_pk_fma_f32 v[2:3], v[30:31], v[138:139], v[2:3] op_sel:[1,0,0]
	v_pk_fma_f32 v[4:5], v[30:31], v[140:141], v[4:5] op_sel:[1,0,0]
	v_pk_fma_f32 v[6:7], v[30:31], v[142:143], v[6:7] op_sel:[1,0,0]
	v_pk_fma_f32 v[8:9], v[30:31], v[152:153], v[8:9] op_sel:[1,0,0]
	v_pk_fma_f32 v[10:11], v[30:31], v[154:155], v[10:11] op_sel:[1,0,0]
	v_pk_fma_f32 v[12:13], v[30:31], v[156:157], v[12:13] op_sel:[1,0,0]
	v_pk_fma_f32 v[14:15], v[30:31], v[158:159], v[14:15] op_sel:[1,0,0]
	s_cmpk_eq_i32 s0, 0x100
	s_cbranch_scc0 .LBB0_1080
	s_add_i32 s22, s22, 1
	v_add_u32_e32 v28, s23, v21
	s_add_u32 s14, s14, 0x1000
	v_ashrrev_i32_e32 v29, 31, v28
	s_addc_u32 s15, s15, 0
	v_lshl_add_u64 v[28:29], v[28:29], 2, s[8:9]
	s_cmp_eq_u32 s22, 7
	s_barrier
	ds_write_b128 v20, v[0:3]
	global_store_dwordx4 v[28:29], v[0:3], off
	ds_write_b128 v20, v[4:7] offset:16
	global_store_dwordx4 v[28:29], v[4:7], off offset:16
	ds_write_b128 v20, v[8:11] offset:32
	global_store_dwordx4 v[28:29], v[8:11], off offset:32
	ds_write_b128 v20, v[12:15] offset:48
	global_store_dwordx4 v[28:29], v[12:15], off offset:48
	s_waitcnt lgkmcnt(0)
	s_barrier
	s_cbranch_scc0 .LBB0_1069
	s_waitcnt vmcnt(0)
	v_cmp_eq_u32_e32 vcc, 0, v16
	s_barrier
	s_and_saveexec_b64 s[0:1], vcc
	s_xor_b64 s[0:1], exec, s[0:1]
	s_cbranch_execz .LBB0_802
	s_mov_b64 s[2:3], exec
	buffer_wbl2 sc1
	s_waitcnt vmcnt(0)
	s_waitcnt vmcnt(0)
	v_mbcnt_lo_u32_b32 v0, s2, 0
	v_mbcnt_hi_u32_b32 v0, s3, v0
	v_cmp_eq_u32_e32 vcc, 0, v0
	s_and_saveexec_b64 s[4:5], vcc
	s_xor_b64 s[4:5], exec, s[4:5]
	s_cbranch_execz .LBB0_801
	s_bcnt1_i32_b64 s2, s[2:3]
	v_mov_b32_e32 v0, s2
	global_atomic_add v149, v0, s[26:27] offset:16
	s_branch .LBB0_801
